# 3-stage merge GEMM prologues: the compiler's wait-for-all right after the stage-0 loads dropped, so stage 0 and stage 1 are in flight together
# speedup vs baseline: 1.0419x; 1.0036x over previous
.LBB0_732:
	v_mov_b32_e32 v20, v198
	s_ashr_i32 s3, s2, 31
	s_lshl_b64 s[12:13], s[2:3], 11
	v_ashrrev_i32_e32 v21, 6, v20
	v_bfe_u32 v0, v20, 3, 3
	s_lshl_b32 s3, s52, 10
	v_lshl_or_b32 v0, v21, 3, v0
	s_add_i32 s54, s3, s6
	v_lshrrev_b32_e32 v23, 1, v0
	s_ashr_i32 s55, s54, 31
	v_xor_b32_e32 v6, v23, v20
	v_ashrrev_i32_e32 v1, 31, v0
	s_lshl_b64 s[54:55], s[54:55], 11
	v_lshlrev_b64 v[2:3], 11, v[0:1]
	v_lshlrev_b32_e32 v1, 4, v6
	v_add_u32_e32 v6, 64, v0
	v_add_u32_e32 v10, 0x80, v0
	v_add_u32_e32 v0, 0xc0, v0
	s_add_u32 s54, s16, s54
	v_and_b32_e32 v64, 0x70, v1
	v_ashrrev_i32_e32 v7, 31, v6
	v_ashrrev_i32_e32 v11, 31, v10
	v_ashrrev_i32_e32 v1, 31, v0
	s_addc_u32 s55, s17, s55
	v_lshlrev_b64 v[6:7], 11, v[6:7]
	v_lshlrev_b64 v[10:11], 11, v[10:11]
	v_lshlrev_b64 v[0:1], 11, v[0:1]
	v_lshl_add_u64 v[4:5], s[8:9], 0, v[2:3]
	v_lshl_add_u64 v[8:9], s[8:9], 0, v[6:7]
	v_lshl_add_u64 v[12:13], s[8:9], 0, v[10:11]
	v_lshl_add_u64 v[14:15], s[8:9], 0, v[0:1]
	v_lshl_add_u64 v[16:17], s[54:55], 0, v[2:3]
	v_lshl_add_u64 v[18:19], s[54:55], 0, v[6:7]
	v_lshl_add_u64 v[4:5], v[4:5], 0, v[64:65]
	v_lshl_add_u64 v[8:9], v[8:9], 0, v[64:65]
	v_lshl_add_u64 v[12:13], v[12:13], 0, v[64:65]
	v_lshl_add_u64 v[14:15], v[14:15], 0, v[64:65]
	v_lshl_add_u64 v[16:17], v[16:17], 0, v[64:65]
	v_lshl_add_u64 v[18:19], v[18:19], 0, v[64:65]
	v_lshl_add_u32 v64, v21, 10, 0
	v_bfe_u32 v24, v20, 4, 2
	v_readfirstlane_b32 s3, v64
	s_mov_b32 m0, s3
	v_bfe_u32 v25, v20, 1, 3
	global_load_lds_dwordx4 v[4:5], off
	v_add_u32_e32 v4, 0x2000, v64
	s_add_u32 s12, s23, s12
	v_readfirstlane_b32 s3, v4
	v_add_u32_e32 v4, 0x4000, v64
	s_mov_b32 m0, s3
	v_readfirstlane_b32 s3, v4
	v_add_u32_e32 v4, 0x6000, v64
	global_load_lds_dwordx4 v[8:9], off
	s_mov_b32 m0, s3
	v_readfirstlane_b32 s3, v4
	v_add_u32_e32 v4, 0x8000, v64
	global_load_lds_dwordx4 v[12:13], off
	s_mov_b32 m0, s3
	v_readfirstlane_b32 s3, v4
	v_add_u32_e32 v4, 0xa000, v64
	global_load_lds_dwordx4 v[14:15], off
	s_mov_b32 m0, s3
	v_readfirstlane_b32 s3, v4
	global_load_lds_dwordx4 v[16:17], off
	s_mov_b32 m0, s3
	v_lshrrev_b32_e32 v4, 31, v20
	global_load_lds_dwordx4 v[18:19], off
	v_add_u32_e32 v4, v21, v4
	v_and_b32_e32 v5, 0x7fffe, v4
	v_lshlrev_b32_e32 v4, 12, v4
	v_and_b32_e32 v144, 0xffffe000, v4
	v_xor_b32_e32 v4, v24, v25
	v_lshlrev_b32_e32 v145, 4, v4
	v_bitop3_b32 v4, v24, v25, 4 bitop3:0x36
	v_lshlrev_b32_e32 v146, 4, v4
	v_bitop3_b32 v4, v23, 7, v20 bitop3:0x48
	v_lshlrev_b32_e32 v4, 4, v4
	v_and_b32_e32 v22, 15, v20
	v_sub_u32_e32 v5, v21, v5
	v_or_b32_e32 v2, v2, v4
	v_or_b32_e32 v6, v6, v4
	v_or_b32_e32 v10, v10, v4
	v_or_b32_e32 v0, v0, v4
	s_addc_u32 s13, s24, s13
	v_mov_b32_e32 v8, 0
	v_lshlrev_b32_e32 v142, 13, v5
	v_lshlrev_b32_e32 v143, 7, v22
	v_lshl_add_u64 v[130:131], s[10:11], 0, v[2:3]
	v_lshl_add_u64 v[132:133], s[10:11], 0, v[6:7]
	v_lshl_add_u64 v[134:135], s[10:11], 0, v[10:11]
	v_lshl_add_u64 v[136:137], s[10:11], 0, v[0:1]
	v_lshl_add_u64 v[138:139], s[12:13], 0, v[2:3]
	v_lshl_add_u64 v[140:141], s[12:13], 0, v[6:7]
	s_mov_b64 s[12:13], 0
	s_mov_b32 s3, 0
	v_mov_b32_e32 v9, v8
	v_mov_b32_e32 v10, v8
	v_mov_b32_e32 v11, v8
	v_mov_b32_e32 v0, v8
	v_mov_b32_e32 v1, v8
	v_mov_b32_e32 v2, v8
	v_mov_b32_e32 v3, v8
	v_mov_b32_e32 v4, v8
	v_mov_b32_e32 v5, v8
	v_mov_b32_e32 v6, v8
	v_mov_b32_e32 v7, v8
	v_mov_b32_e32 v12, v8
	v_mov_b32_e32 v13, v8
	v_mov_b32_e32 v14, v8
	v_mov_b32_e32 v15, v8
	v_mov_b32_e32 v16, v8
	v_mov_b32_e32 v17, v8
	v_mov_b32_e32 v18, v8
	v_mov_b32_e32 v19, v8
	v_mov_b32_e32 v20, v8
	v_mov_b32_e32 v21, v8
	v_mov_b32_e32 v22, v8
	v_mov_b32_e32 v23, v8
	v_mov_b32_e32 v24, v8
	v_mov_b32_e32 v25, v8
	v_mov_b32_e32 v26, v8
	v_mov_b32_e32 v27, v8
	v_mov_b32_e32 v28, v8
	v_mov_b32_e32 v29, v8
	v_mov_b32_e32 v30, v8
	v_mov_b32_e32 v31, v8
	v_mov_b32_e32 v32, v8
	v_mov_b32_e32 v33, v8
	v_mov_b32_e32 v34, v8
	v_mov_b32_e32 v35, v8
	v_mov_b32_e32 v36, v8
	v_mov_b32_e32 v37, v8
	v_mov_b32_e32 v38, v8
	v_mov_b32_e32 v39, v8
	v_mov_b32_e32 v40, v8
	v_mov_b32_e32 v41, v8
	v_mov_b32_e32 v42, v8
	v_mov_b32_e32 v43, v8
	v_mov_b32_e32 v44, v8
	v_mov_b32_e32 v45, v8
	v_mov_b32_e32 v46, v8
	v_mov_b32_e32 v47, v8
	v_mov_b32_e32 v48, v8
	v_mov_b32_e32 v49, v8
	v_mov_b32_e32 v50, v8
	v_mov_b32_e32 v51, v8
	v_mov_b32_e32 v52, v8
	v_mov_b32_e32 v53, v8
	v_mov_b32_e32 v54, v8
	v_mov_b32_e32 v55, v8
	v_mov_b32_e32 v56, v8
	v_mov_b32_e32 v57, v8
	v_mov_b32_e32 v58, v8
	v_mov_b32_e32 v59, v8
	v_mov_b32_e32 v60, v8
	v_mov_b32_e32 v61, v8
	v_mov_b32_e32 v62, v8
	v_mov_b32_e32 v63, v8
	v_readfirstlane_b32 s54, v64
	s_nop 1
	s_add_i32 s54, s54, 0xc000
	s_mov_b32 m0, s54
	s_nop 0
	global_load_lds_dwordx4 v[130:131], off
	s_add_i32 m0, s54, 0x2000
	s_nop 0
	global_load_lds_dwordx4 v[132:133], off
	s_add_i32 m0, s54, 0x4000
	s_nop 0
	global_load_lds_dwordx4 v[134:135], off
	s_add_i32 m0, s54, 0x6000
	s_nop 0
	global_load_lds_dwordx4 v[136:137], off
	s_add_i32 m0, s54, 0x8000
	s_nop 0
	global_load_lds_dwordx4 v[138:139], off
	s_add_i32 m0, s54, 0xa000
	s_nop 0
	global_load_lds_dwordx4 v[140:141], off
	s_waitcnt vmcnt(6) lgkmcnt(0)
	s_barrier
	s_branch .LBB0_734

.LBB0_736:
	s_nop 5
	v_mul_f32_e32 v0, 0xbfb8aa3b, v0
	v_exp_f32_e32 v0, v0
	v_mul_f32_e32 v1, 0xbfb8aa3b, v1
	v_exp_f32_e32 v1, v1
	v_mul_f32_e32 v20, 0xbfb8aa3b, v20
	v_add_f32_e32 v0, 1.0, v0
	v_rcp_f32_e32 v204, v0
	v_add_f32_e32 v0, 1.0, v1
	v_mul_f32_e32 v1, 0xbfb8aa3b, v2
	v_exp_f32_e32 v1, v1
	v_mul_f32_e32 v2, 0xbfb8aa3b, v3
	v_exp_f32_e32 v2, v2
	v_exp_f32_e32 v20, v20
	v_mul_f32_e32 v21, 0xbfb8aa3b, v21
	v_exp_f32_e32 v21, v21
	v_rcp_f32_e32 v205, v0
	v_add_f32_e32 v0, 1.0, v1
	v_mul_f32_e32 v1, 0xbfb8aa3b, v8
	v_rcp_f32_e32 v192, v0
	v_add_f32_e32 v0, 1.0, v2
	v_exp_f32_e32 v1, v1
	v_mul_f32_e32 v2, 0xbfb8aa3b, v9
	v_exp_f32_e32 v2, v2
	v_add_f32_e32 v20, 1.0, v20
	v_mul_f32_e32 v4, 0xbfb8aa3b, v4
	v_mul_f32_e32 v24, 0xbfb8aa3b, v24
	v_rcp_f32_e32 v189, v20
	v_add_f32_e32 v20, 1.0, v21
	v_mul_f32_e32 v21, 0xbfb8aa3b, v22
	v_exp_f32_e32 v4, v4
	v_mul_f32_e32 v5, 0xbfb8aa3b, v5
	v_exp_f32_e32 v24, v24
	v_mul_f32_e32 v25, 0xbfb8aa3b, v25
	v_exp_f32_e32 v21, v21
	v_mul_f32_e32 v22, 0xbfb8aa3b, v23
	v_exp_f32_e32 v5, v5
	v_rcp_f32_e32 v194, v0
	v_add_f32_e32 v0, 1.0, v1
	v_mul_f32_e32 v1, 0xbfb8aa3b, v10
	v_exp_f32_e32 v25, v25
	v_exp_f32_e32 v22, v22
	v_rcp_f32_e32 v206, v0
	v_add_f32_e32 v0, 1.0, v2
	v_exp_f32_e32 v1, v1
	v_mul_f32_e32 v2, 0xbfb8aa3b, v11
	v_exp_f32_e32 v2, v2
	v_add_f32_e32 v4, 1.0, v4
	v_add_f32_e32 v24, 1.0, v24
	v_rcp_f32_e32 v191, v20
	v_add_f32_e32 v20, 1.0, v21
	v_rcp_f32_e32 v202, v4
	v_add_f32_e32 v4, 1.0, v5
	v_mul_f32_e32 v5, 0xbfb8aa3b, v6
	v_rcp_f32_e32 v185, v24
	v_add_f32_e32 v24, 1.0, v25
	v_mul_f32_e32 v25, 0xbfb8aa3b, v26
	v_rcp_f32_e32 v176, v20
	v_add_f32_e32 v20, 1.0, v22
	v_exp_f32_e32 v5, v5
	v_mul_f32_e32 v6, 0xbfb8aa3b, v7
	v_rcp_f32_e32 v207, v0
	v_add_f32_e32 v0, 1.0, v1
	s_cmp_eq_u32 s52, 1
	v_exp_f32_e32 v25, v25
	v_mul_f32_e32 v26, 0xbfb8aa3b, v27
	v_rcp_f32_e32 v178, v20
	v_exp_f32_e32 v6, v6
	v_rcp_f32_e32 v196, v0
	v_add_f32_e32 v0, 1.0, v2
	v_mov_b32_e32 v20, v198
	v_exp_f32_e32 v26, v26
	v_rcp_f32_e32 v197, v0
	s_cselect_b32 s12, s34, 0x1200
	s_cmp_lg_u32 s52, 0
	v_mul_f32_e32 v12, 0xbfb8aa3b, v12
	v_ashrrev_i32_e32 v21, 6, v20
	v_bfe_u32 v0, v20, 3, 3
	s_cselect_b32 s12, s12, 0x600
	v_lshl_or_b32 v0, v21, 3, v0
	v_mul_f32_e32 v16, 0xbfb8aa3b, v16
	v_exp_f32_e32 v12, v12
	v_mul_f32_e32 v13, 0xbfb8aa3b, v13
	v_rcp_f32_e32 v203, v4
	v_add_f32_e32 v4, 1.0, v5
	s_lshl_b32 s53, s12, 1
	v_lshrrev_b32_e32 v23, 1, v0
	v_rcp_f32_e32 v187, v24
	v_add_f32_e32 v24, 1.0, v25
	v_exp_f32_e32 v16, v16
	v_mul_f32_e32 v17, 0xbfb8aa3b, v17
	v_exp_f32_e32 v13, v13
	v_rcp_f32_e32 v188, v4
	v_add_f32_e32 v4, 1.0, v6
	s_add_u32 s12, s38, s53
	v_xor_b32_e32 v6, v23, v20
	v_rcp_f32_e32 v172, v24
	v_add_f32_e32 v24, 1.0, v26
	v_exp_f32_e32 v17, v17
	s_addc_u32 s13, s39, 0
	v_lshlrev_b32_e32 v6, 4, v6
	v_rcp_f32_e32 v174, v24
	v_mov_b64_e32 v[2:3], s[12:13]
	v_and_b32_e32 v64, 0x70, v6
	v_add_u32_e32 v6, 64, v0
	v_add_u32_e32 v24, 0x80, v0
	v_add_u32_e32 v25, 0xc0, v0
	v_add_f32_e32 v12, 1.0, v12
	v_rcp_f32_e32 v190, v4
	v_mad_i64_i32 v[4:5], s[12:13], v0, s35, v[2:3]
	v_mad_i64_i32 v[8:9], s[12:13], v6, s35, v[2:3]
	v_mad_i64_i32 v[10:11], s[12:13], v24, s35, v[2:3]
	v_mad_i64_i32 v[2:3], s[12:13], v25, s35, v[2:3]
	v_lshl_add_u32 v208, v21, 10, 0
	v_add_f32_e32 v16, 1.0, v16
	v_rcp_f32_e32 v200, v12
	v_add_f32_e32 v12, 1.0, v13
	v_mul_f32_e32 v13, 0xbfb8aa3b, v14
	v_readfirstlane_b32 s12, v208
	v_rcp_f32_e32 v193, v16
	v_add_f32_e32 v16, 1.0, v17
	v_mul_f32_e32 v17, 0xbfb8aa3b, v18
	v_exp_f32_e32 v13, v13
	v_mul_f32_e32 v14, 0xbfb8aa3b, v15
	v_lshl_add_u64 v[4:5], v[4:5], 0, v[64:65]
	s_mov_b32 m0, s12
	v_exp_f32_e32 v17, v17
	v_mul_f32_e32 v18, 0xbfb8aa3b, v19
	v_exp_f32_e32 v14, v14
	global_load_lds_dwordx4 v[4:5], off
	v_add_u32_e32 v4, 0x2000, v208
	v_exp_f32_e32 v18, v18
	v_readfirstlane_b32 s12, v4
	v_add_u32_e32 v4, 0x4000, v208
	v_lshl_add_u64 v[8:9], v[8:9], 0, v[64:65]
	s_mov_b32 m0, s12
	v_readfirstlane_b32 s12, v4
	v_add_u32_e32 v4, 0x6000, v208
	v_rcp_f32_e32 v201, v12
	v_add_f32_e32 v12, 1.0, v13
	s_lshl_b32 s54, s52, 20
	v_lshl_add_u64 v[10:11], v[10:11], 0, v[64:65]
	global_load_lds_dwordx4 v[8:9], off
	s_mov_b32 m0, s12
	v_readfirstlane_b32 s12, v4
	v_rcp_f32_e32 v195, v16
	v_add_f32_e32 v16, 1.0, v17
	v_rcp_f32_e32 v184, v12
	v_add_f32_e32 v12, 1.0, v14
	s_add_u32 s54, s40, s54
	v_ashrrev_i32_e32 v1, 31, v0
	v_lshl_add_u64 v[2:3], v[2:3], 0, v[64:65]
	global_load_lds_dwordx4 v[10:11], off
	s_mov_b32 m0, s12
	v_rcp_f32_e32 v180, v16
	v_add_f32_e32 v16, 1.0, v18
	v_rcp_f32_e32 v186, v12
	s_addc_u32 s55, s41, 0
	v_ashrrev_i32_e32 v7, 31, v6
	v_lshlrev_b64 v[12:13], 10, v[0:1]
	global_load_lds_dwordx4 v[2:3], off
	v_add_u32_e32 v2, 0x8000, v208
	v_rcp_f32_e32 v182, v16
	v_lshl_add_u64 v[14:15], s[54:55], 0, v[12:13]
	v_lshlrev_b64 v[16:17], 10, v[6:7]
	v_readfirstlane_b32 s12, v2
	v_add_u32_e32 v2, 0xa000, v208
	v_lshl_add_u64 v[14:15], v[14:15], 0, v[64:65]
	v_lshl_add_u64 v[18:19], s[54:55], 0, v[16:17]
	s_mov_b32 m0, s12
	v_readfirstlane_b32 s12, v2
	v_lshl_add_u64 v[18:19], v[18:19], 0, v[64:65]
	global_load_lds_dwordx4 v[14:15], off
	s_mov_b32 m0, s12
	v_mul_f32_e32 v60, 0xbfb8aa3b, v60
	global_load_lds_dwordx4 v[18:19], off
	v_mul_f32_e32 v56, 0xbfb8aa3b, v56
	v_mul_f32_e32 v52, 0xbfb8aa3b, v52
	v_mul_f32_e32 v48, 0xbfb8aa3b, v48
	v_mul_f32_e32 v44, 0xbfb8aa3b, v44
	v_mul_f32_e32 v40, 0xbfb8aa3b, v40
	v_mul_f32_e32 v36, 0xbfb8aa3b, v36
	v_mul_f32_e32 v32, 0xbfb8aa3b, v32
	v_mul_f32_e32 v28, 0xbfb8aa3b, v28
	v_exp_f32_e32 v60, v60
	v_mul_f32_e32 v61, 0xbfb8aa3b, v61
	v_exp_f32_e32 v56, v56
	v_mul_f32_e32 v57, 0xbfb8aa3b, v57
	v_exp_f32_e32 v52, v52
	v_mul_f32_e32 v53, 0xbfb8aa3b, v53
	v_exp_f32_e32 v48, v48
	v_mul_f32_e32 v49, 0xbfb8aa3b, v49
	v_exp_f32_e32 v44, v44
	v_mul_f32_e32 v45, 0xbfb8aa3b, v45
	v_exp_f32_e32 v40, v40
	v_mul_f32_e32 v41, 0xbfb8aa3b, v41
	v_exp_f32_e32 v36, v36
	v_mul_f32_e32 v37, 0xbfb8aa3b, v37
	v_exp_f32_e32 v32, v32
	v_mul_f32_e32 v33, 0xbfb8aa3b, v33
	v_exp_f32_e32 v28, v28
	v_mul_f32_e32 v29, 0xbfb8aa3b, v29
	v_exp_f32_e32 v61, v61
	v_exp_f32_e32 v57, v57
	v_exp_f32_e32 v53, v53
	v_exp_f32_e32 v49, v49
	v_exp_f32_e32 v45, v45
	v_exp_f32_e32 v41, v41
	v_exp_f32_e32 v37, v37
	v_exp_f32_e32 v33, v33
	v_exp_f32_e32 v29, v29
	v_lshrrev_b32_e32 v2, 31, v20
	v_add_u32_e32 v2, v21, v2
	v_add_f32_e32 v60, 1.0, v60
	v_add_f32_e32 v56, 1.0, v56
	v_add_f32_e32 v52, 1.0, v52
	v_add_f32_e32 v48, 1.0, v48
	v_add_f32_e32 v44, 1.0, v44
	v_add_f32_e32 v40, 1.0, v40
	v_add_f32_e32 v36, 1.0, v36
	v_add_f32_e32 v32, 1.0, v32
	v_add_f32_e32 v28, 1.0, v28
	v_bfe_u32 v1, v20, 4, 2
	v_bfe_u32 v7, v20, 1, 3
	v_and_b32_e32 v3, 0x7fffe, v2
	v_lshlrev_b32_e32 v2, 12, v2
	v_rcp_f32_e32 v149, v60
	v_add_f32_e32 v60, 1.0, v61
	v_mul_f32_e32 v61, 0xbfb8aa3b, v62
	v_rcp_f32_e32 v153, v56
	v_add_f32_e32 v56, 1.0, v57
	v_mul_f32_e32 v57, 0xbfb8aa3b, v58
	v_rcp_f32_e32 v157, v52
	v_add_f32_e32 v52, 1.0, v53
	v_mul_f32_e32 v53, 0xbfb8aa3b, v54
	v_rcp_f32_e32 v161, v48
	v_add_f32_e32 v48, 1.0, v49
	v_mul_f32_e32 v49, 0xbfb8aa3b, v50
	v_rcp_f32_e32 v165, v44
	v_add_f32_e32 v44, 1.0, v45
	v_mul_f32_e32 v45, 0xbfb8aa3b, v46
	v_rcp_f32_e32 v169, v40
	v_add_f32_e32 v40, 1.0, v41
	v_mul_f32_e32 v41, 0xbfb8aa3b, v42
	v_rcp_f32_e32 v173, v36
	v_add_f32_e32 v36, 1.0, v37
	v_mul_f32_e32 v37, 0xbfb8aa3b, v38
	v_rcp_f32_e32 v177, v32
	v_add_f32_e32 v32, 1.0, v33
	v_mul_f32_e32 v33, 0xbfb8aa3b, v34
	v_rcp_f32_e32 v181, v28
	v_add_f32_e32 v28, 1.0, v29
	v_mul_f32_e32 v29, 0xbfb8aa3b, v30
	v_and_b32_e32 v211, 0xffffe000, v2
	v_xor_b32_e32 v2, v1, v7
	v_bitop3_b32 v1, v1, v7, 4 bitop3:0x36
	v_exp_f32_e32 v61, v61
	v_mul_f32_e32 v62, 0xbfb8aa3b, v63
	v_exp_f32_e32 v57, v57
	v_mul_f32_e32 v58, 0xbfb8aa3b, v59
	v_exp_f32_e32 v53, v53
	v_mul_f32_e32 v54, 0xbfb8aa3b, v55
	v_exp_f32_e32 v49, v49
	v_mul_f32_e32 v50, 0xbfb8aa3b, v51
	v_exp_f32_e32 v45, v45
	v_mul_f32_e32 v46, 0xbfb8aa3b, v47
	v_exp_f32_e32 v41, v41
	v_mul_f32_e32 v42, 0xbfb8aa3b, v43
	v_exp_f32_e32 v37, v37
	v_mul_f32_e32 v38, 0xbfb8aa3b, v39
	v_exp_f32_e32 v33, v33
	v_mul_f32_e32 v34, 0xbfb8aa3b, v35
	v_exp_f32_e32 v29, v29
	v_mul_f32_e32 v30, 0xbfb8aa3b, v31
	v_lshlrev_b32_e32 v213, 4, v1
	v_bitop3_b32 v1, v23, 7, v20 bitop3:0x48
	v_exp_f32_e32 v62, v62
	v_exp_f32_e32 v58, v58
	v_exp_f32_e32 v54, v54
	v_exp_f32_e32 v50, v50
	v_exp_f32_e32 v46, v46
	v_exp_f32_e32 v42, v42
	v_exp_f32_e32 v38, v38
	v_exp_f32_e32 v34, v34
	v_exp_f32_e32 v30, v30
	v_lshlrev_b32_e32 v64, 4, v1
	v_mad_i64_i32 v[0:1], s[12:13], v0, s35, v[64:65]
	s_add_u32 s12, s42, s53
	v_rcp_f32_e32 v151, v60
	v_add_f32_e32 v60, 1.0, v61
	v_rcp_f32_e32 v155, v56
	v_add_f32_e32 v56, 1.0, v57
	v_rcp_f32_e32 v159, v52
	v_add_f32_e32 v52, 1.0, v53
	v_rcp_f32_e32 v163, v48
	v_add_f32_e32 v48, 1.0, v49
	v_rcp_f32_e32 v167, v44
	v_add_f32_e32 v44, 1.0, v45
	v_rcp_f32_e32 v171, v40
	v_add_f32_e32 v40, 1.0, v41
	v_rcp_f32_e32 v175, v36
	v_add_f32_e32 v36, 1.0, v37
	v_rcp_f32_e32 v179, v32
	v_add_f32_e32 v32, 1.0, v33
	v_rcp_f32_e32 v183, v28
	v_add_f32_e32 v28, 1.0, v29
	s_addc_u32 s13, s43, 0
	v_rcp_f32_e32 v142, v60
	v_add_f32_e32 v60, 1.0, v62
	v_rcp_f32_e32 v144, v56
	v_add_f32_e32 v56, 1.0, v58
	v_rcp_f32_e32 v146, v52
	v_add_f32_e32 v52, 1.0, v54
	v_rcp_f32_e32 v148, v48
	v_add_f32_e32 v48, 1.0, v50
	v_rcp_f32_e32 v152, v44
	v_add_f32_e32 v44, 1.0, v46
	v_rcp_f32_e32 v156, v40
	v_add_f32_e32 v40, 1.0, v42
	v_rcp_f32_e32 v160, v36
	v_add_f32_e32 v36, 1.0, v38
	v_rcp_f32_e32 v164, v32
	v_add_f32_e32 v32, 1.0, v34
	v_rcp_f32_e32 v168, v28
	v_add_f32_e32 v28, 1.0, v30
	v_lshl_add_u64 v[130:131], s[12:13], 0, v[0:1]
	v_mad_i64_i32 v[0:1], s[54:55], v6, s35, v[64:65]
	v_rcp_f32_e32 v143, v60
	v_rcp_f32_e32 v145, v56
	v_rcp_f32_e32 v147, v52
	v_rcp_f32_e32 v150, v48
	v_rcp_f32_e32 v154, v44
	v_rcp_f32_e32 v158, v40
	v_rcp_f32_e32 v162, v36
	v_rcp_f32_e32 v166, v32
	v_rcp_f32_e32 v170, v28
	v_lshl_add_u64 v[132:133], s[12:13], 0, v[0:1]
	v_mad_i64_i32 v[0:1], s[54:55], v24, s35, v[64:65]
	v_lshl_add_u64 v[134:135], s[12:13], 0, v[0:1]
	v_mad_i64_i32 v[0:1], s[54:55], v25, s35, v[64:65]
	v_and_b32_e32 v22, 15, v20
	v_sub_u32_e32 v3, v21, v3
	v_lshl_add_u64 v[136:137], s[12:13], 0, v[0:1]
	v_or_b32_e32 v12, v12, v64
	v_or_b32_e32 v16, v16, v64
	v_mov_b32_e32 v0, 0
	s_mov_b32 s3, 0
	v_lshlrev_b32_e32 v209, 13, v3
	v_lshlrev_b32_e32 v210, 7, v22
	v_lshlrev_b32_e32 v212, 4, v2
	v_lshl_add_u64 v[138:139], s[4:5], 0, v[12:13]
	v_lshl_add_u64 v[140:141], s[4:5], 0, v[16:17]
	s_mov_b64 s[12:13], 0
	v_mov_b32_e32 v1, v0
	v_mov_b32_e32 v2, v0
	v_mov_b32_e32 v3, v0
	v_mov_b32_e32 v4, v0
	v_mov_b32_e32 v5, v0
	v_mov_b32_e32 v6, v0
	v_mov_b32_e32 v7, v0
	v_mov_b32_e32 v8, v0
	v_mov_b32_e32 v9, v0
	v_mov_b32_e32 v10, v0
	v_mov_b32_e32 v11, v0
	v_mov_b32_e32 v12, v0
	v_mov_b32_e32 v13, v0
	v_mov_b32_e32 v14, v0
	v_mov_b32_e32 v15, v0
	v_mov_b32_e32 v16, v0
	v_mov_b32_e32 v17, v0
	v_mov_b32_e32 v18, v0
	v_mov_b32_e32 v19, v0
	v_mov_b32_e32 v20, v0
	v_mov_b32_e32 v21, v0
	v_mov_b32_e32 v22, v0
	v_mov_b32_e32 v23, v0
	v_mov_b32_e32 v24, v0
	v_mov_b32_e32 v25, v0
	v_mov_b32_e32 v26, v0
	v_mov_b32_e32 v27, v0
	v_mov_b32_e32 v28, v0
	v_mov_b32_e32 v29, v0
	v_mov_b32_e32 v30, v0
	v_mov_b32_e32 v31, v0
	v_mov_b32_e32 v32, v0
	v_mov_b32_e32 v33, v0
	v_mov_b32_e32 v34, v0
	v_mov_b32_e32 v35, v0
	v_mov_b32_e32 v36, v0
	v_mov_b32_e32 v37, v0
	v_mov_b32_e32 v38, v0
	v_mov_b32_e32 v39, v0
	v_mov_b32_e32 v40, v0
	v_mov_b32_e32 v41, v0
	v_mov_b32_e32 v42, v0
	v_mov_b32_e32 v43, v0
	v_mov_b32_e32 v44, v0
	v_mov_b32_e32 v45, v0
	v_mov_b32_e32 v46, v0
	v_mov_b32_e32 v47, v0
	v_mov_b32_e32 v48, v0
	v_mov_b32_e32 v49, v0
	v_mov_b32_e32 v50, v0
	v_mov_b32_e32 v51, v0
	v_mov_b32_e32 v52, v0
	v_mov_b32_e32 v53, v0
	v_mov_b32_e32 v54, v0
	v_mov_b32_e32 v55, v0
	v_mov_b32_e32 v56, v0
	v_mov_b32_e32 v57, v0
	v_mov_b32_e32 v58, v0
	v_mov_b32_e32 v59, v0
	v_mov_b32_e32 v60, v0
	v_mov_b32_e32 v61, v0
	v_mov_b32_e32 v62, v0
	v_mov_b32_e32 v63, v0
	v_readfirstlane_b32 s54, v208
	s_nop 1
	s_add_i32 s54, s54, 0xc000
	s_mov_b32 m0, s54
	s_nop 0
	global_load_lds_dwordx4 v[130:131], off
	s_add_i32 m0, s54, 0x2000
	s_nop 0
	global_load_lds_dwordx4 v[132:133], off
	s_add_i32 m0, s54, 0x4000
	s_nop 0
	global_load_lds_dwordx4 v[134:135], off
	s_add_i32 m0, s54, 0x6000
	s_nop 0
	global_load_lds_dwordx4 v[136:137], off
	s_add_i32 m0, s54, 0x8000
	s_nop 0
	global_load_lds_dwordx4 v[138:139], off
	s_add_i32 m0, s54, 0xa000
	s_nop 0
	global_load_lds_dwordx4 v[140:141], off
	s_waitcnt vmcnt(6) lgkmcnt(0)
	s_barrier
	s_branch .LBB0_738

.LBB0_1498:
	v_mov_b32_e32 v20, v198
	s_ashr_i32 s3, s2, 31
	s_lshl_b64 s[12:13], s[2:3], 11
	v_ashrrev_i32_e32 v21, 6, v20
	v_bfe_u32 v0, v20, 3, 3
	s_lshl_b32 s3, s44, 10
	v_lshl_or_b32 v0, v21, 3, v0
	s_add_i32 s46, s3, s6
	v_lshrrev_b32_e32 v23, 1, v0
	s_ashr_i32 s47, s46, 31
	v_xor_b32_e32 v6, v23, v20
	v_ashrrev_i32_e32 v1, 31, v0
	s_lshl_b64 s[46:47], s[46:47], 11
	v_lshlrev_b64 v[2:3], 11, v[0:1]
	v_lshlrev_b32_e32 v1, 4, v6
	v_add_u32_e32 v6, 64, v0
	v_add_u32_e32 v10, 0x80, v0
	v_add_u32_e32 v0, 0xc0, v0
	s_add_u32 s46, s16, s46
	v_and_b32_e32 v64, 0x70, v1
	v_ashrrev_i32_e32 v7, 31, v6
	v_ashrrev_i32_e32 v11, 31, v10
	v_ashrrev_i32_e32 v1, 31, v0
	s_addc_u32 s47, s17, s47
	v_lshlrev_b64 v[6:7], 11, v[6:7]
	v_lshlrev_b64 v[10:11], 11, v[10:11]
	v_lshlrev_b64 v[0:1], 11, v[0:1]
	v_lshl_add_u64 v[4:5], s[8:9], 0, v[2:3]
	v_lshl_add_u64 v[8:9], s[8:9], 0, v[6:7]
	v_lshl_add_u64 v[12:13], s[8:9], 0, v[10:11]
	v_lshl_add_u64 v[14:15], s[8:9], 0, v[0:1]
	v_lshl_add_u64 v[16:17], s[46:47], 0, v[2:3]
	v_lshl_add_u64 v[18:19], s[46:47], 0, v[6:7]
	v_lshl_add_u64 v[4:5], v[4:5], 0, v[64:65]
	v_lshl_add_u64 v[8:9], v[8:9], 0, v[64:65]
	v_lshl_add_u64 v[12:13], v[12:13], 0, v[64:65]
	v_lshl_add_u64 v[14:15], v[14:15], 0, v[64:65]
	v_lshl_add_u64 v[16:17], v[16:17], 0, v[64:65]
	v_lshl_add_u64 v[18:19], v[18:19], 0, v[64:65]
	v_lshl_add_u32 v64, v21, 10, 0
	v_bfe_u32 v24, v20, 4, 2
	v_readfirstlane_b32 s3, v64
	s_mov_b32 m0, s3
	v_bfe_u32 v25, v20, 1, 3
	global_load_lds_dwordx4 v[4:5], off
	v_add_u32_e32 v4, 0x2000, v64
	s_add_u32 s12, s23, s12
	v_readfirstlane_b32 s3, v4
	v_add_u32_e32 v4, 0x4000, v64
	s_mov_b32 m0, s3
	v_readfirstlane_b32 s3, v4
	v_add_u32_e32 v4, 0x6000, v64
	global_load_lds_dwordx4 v[8:9], off
	s_mov_b32 m0, s3
	v_readfirstlane_b32 s3, v4
	v_add_u32_e32 v4, 0x8000, v64
	global_load_lds_dwordx4 v[12:13], off
	s_mov_b32 m0, s3
	v_readfirstlane_b32 s3, v4
	v_add_u32_e32 v4, 0xa000, v64
	global_load_lds_dwordx4 v[14:15], off
	s_mov_b32 m0, s3
	v_readfirstlane_b32 s3, v4
	global_load_lds_dwordx4 v[16:17], off
	s_mov_b32 m0, s3
	v_lshrrev_b32_e32 v4, 31, v20
	global_load_lds_dwordx4 v[18:19], off
	v_add_u32_e32 v4, v21, v4
	v_and_b32_e32 v5, 0x7fffe, v4
	v_lshlrev_b32_e32 v4, 12, v4
	v_and_b32_e32 v144, 0xffffe000, v4
	v_xor_b32_e32 v4, v24, v25
	v_lshlrev_b32_e32 v145, 4, v4
	v_bitop3_b32 v4, v24, v25, 4 bitop3:0x36
	v_lshlrev_b32_e32 v146, 4, v4
	v_bitop3_b32 v4, v23, 7, v20 bitop3:0x48
	v_lshlrev_b32_e32 v4, 4, v4
	v_and_b32_e32 v22, 15, v20
	v_sub_u32_e32 v5, v21, v5
	v_or_b32_e32 v2, v2, v4
	v_or_b32_e32 v6, v6, v4
	v_or_b32_e32 v10, v10, v4
	v_or_b32_e32 v0, v0, v4
	s_addc_u32 s13, s24, s13
	v_mov_b32_e32 v8, 0
	v_lshlrev_b32_e32 v142, 13, v5
	v_lshlrev_b32_e32 v143, 7, v22
	v_lshl_add_u64 v[130:131], s[10:11], 0, v[2:3]
	v_lshl_add_u64 v[132:133], s[10:11], 0, v[6:7]
	v_lshl_add_u64 v[134:135], s[10:11], 0, v[10:11]
	v_lshl_add_u64 v[136:137], s[10:11], 0, v[0:1]
	v_lshl_add_u64 v[138:139], s[12:13], 0, v[2:3]
	v_lshl_add_u64 v[140:141], s[12:13], 0, v[6:7]
	s_mov_b64 s[12:13], 0
	s_mov_b32 s3, 0
	v_mov_b32_e32 v9, v8
	v_mov_b32_e32 v10, v8
	v_mov_b32_e32 v11, v8
	v_mov_b32_e32 v0, v8
	v_mov_b32_e32 v1, v8
	v_mov_b32_e32 v2, v8
	v_mov_b32_e32 v3, v8
	v_mov_b32_e32 v4, v8
	v_mov_b32_e32 v5, v8
	v_mov_b32_e32 v6, v8
	v_mov_b32_e32 v7, v8
	v_mov_b32_e32 v12, v8
	v_mov_b32_e32 v13, v8
	v_mov_b32_e32 v14, v8
	v_mov_b32_e32 v15, v8
	v_mov_b32_e32 v16, v8
	v_mov_b32_e32 v17, v8
	v_mov_b32_e32 v18, v8
	v_mov_b32_e32 v19, v8
	v_mov_b32_e32 v20, v8
	v_mov_b32_e32 v21, v8
	v_mov_b32_e32 v22, v8
	v_mov_b32_e32 v23, v8
	v_mov_b32_e32 v24, v8
	v_mov_b32_e32 v25, v8
	v_mov_b32_e32 v26, v8
	v_mov_b32_e32 v27, v8
	v_mov_b32_e32 v28, v8
	v_mov_b32_e32 v29, v8
	v_mov_b32_e32 v30, v8
	v_mov_b32_e32 v31, v8
	v_mov_b32_e32 v32, v8
	v_mov_b32_e32 v33, v8
	v_mov_b32_e32 v34, v8
	v_mov_b32_e32 v35, v8
	v_mov_b32_e32 v36, v8
	v_mov_b32_e32 v37, v8
	v_mov_b32_e32 v38, v8
	v_mov_b32_e32 v39, v8
	v_mov_b32_e32 v40, v8
	v_mov_b32_e32 v41, v8
	v_mov_b32_e32 v42, v8
	v_mov_b32_e32 v43, v8
	v_mov_b32_e32 v44, v8
	v_mov_b32_e32 v45, v8
	v_mov_b32_e32 v46, v8
	v_mov_b32_e32 v47, v8
	v_mov_b32_e32 v48, v8
	v_mov_b32_e32 v49, v8
	v_mov_b32_e32 v50, v8
	v_mov_b32_e32 v51, v8
	v_mov_b32_e32 v52, v8
	v_mov_b32_e32 v53, v8
	v_mov_b32_e32 v54, v8
	v_mov_b32_e32 v55, v8
	v_mov_b32_e32 v56, v8
	v_mov_b32_e32 v57, v8
	v_mov_b32_e32 v58, v8
	v_mov_b32_e32 v59, v8
	v_mov_b32_e32 v60, v8
	v_mov_b32_e32 v61, v8
	v_mov_b32_e32 v62, v8
	v_mov_b32_e32 v63, v8
	v_readfirstlane_b32 s46, v64
	s_nop 1
	s_add_i32 s46, s46, 0xc000
	s_mov_b32 m0, s46
	s_nop 0
	global_load_lds_dwordx4 v[130:131], off
	s_add_i32 m0, s46, 0x2000
	s_nop 0
	global_load_lds_dwordx4 v[132:133], off
	s_add_i32 m0, s46, 0x4000
	s_nop 0
	global_load_lds_dwordx4 v[134:135], off
	s_add_i32 m0, s46, 0x6000
	s_nop 0
	global_load_lds_dwordx4 v[136:137], off
	s_add_i32 m0, s46, 0x8000
	s_nop 0
	global_load_lds_dwordx4 v[138:139], off
	s_add_i32 m0, s46, 0xa000
	s_nop 0
	global_load_lds_dwordx4 v[140:141], off
	s_waitcnt vmcnt(6) lgkmcnt(0)
	s_barrier
	s_branch .LBB0_1500

.LBB0_1502:
	s_nop 5
	v_mul_f32_e32 v0, 0xbfb8aa3b, v0
	v_exp_f32_e32 v0, v0
	v_mul_f32_e32 v1, 0xbfb8aa3b, v1
	v_exp_f32_e32 v1, v1
	v_mul_f32_e32 v20, 0xbfb8aa3b, v20
	v_add_f32_e32 v0, 1.0, v0
	v_rcp_f32_e32 v204, v0
	v_add_f32_e32 v0, 1.0, v1
	v_mul_f32_e32 v1, 0xbfb8aa3b, v2
	v_exp_f32_e32 v1, v1
	v_mul_f32_e32 v2, 0xbfb8aa3b, v3
	v_exp_f32_e32 v2, v2
	v_exp_f32_e32 v20, v20
	v_mul_f32_e32 v21, 0xbfb8aa3b, v21
	v_exp_f32_e32 v21, v21
	v_rcp_f32_e32 v205, v0
	v_add_f32_e32 v0, 1.0, v1
	v_mul_f32_e32 v1, 0xbfb8aa3b, v8
	v_rcp_f32_e32 v192, v0
	v_add_f32_e32 v0, 1.0, v2
	v_exp_f32_e32 v1, v1
	v_mul_f32_e32 v2, 0xbfb8aa3b, v9
	v_exp_f32_e32 v2, v2
	v_add_f32_e32 v20, 1.0, v20
	v_mul_f32_e32 v4, 0xbfb8aa3b, v4
	v_mul_f32_e32 v24, 0xbfb8aa3b, v24
	v_rcp_f32_e32 v189, v20
	v_add_f32_e32 v20, 1.0, v21
	v_mul_f32_e32 v21, 0xbfb8aa3b, v22
	v_exp_f32_e32 v4, v4
	v_mul_f32_e32 v5, 0xbfb8aa3b, v5
	v_exp_f32_e32 v24, v24
	v_mul_f32_e32 v25, 0xbfb8aa3b, v25
	v_exp_f32_e32 v21, v21
	v_mul_f32_e32 v22, 0xbfb8aa3b, v23
	v_exp_f32_e32 v5, v5
	v_rcp_f32_e32 v194, v0
	v_add_f32_e32 v0, 1.0, v1
	v_mul_f32_e32 v1, 0xbfb8aa3b, v10
	v_exp_f32_e32 v25, v25
	v_exp_f32_e32 v22, v22
	v_rcp_f32_e32 v206, v0
	v_add_f32_e32 v0, 1.0, v2
	v_exp_f32_e32 v1, v1
	v_mul_f32_e32 v2, 0xbfb8aa3b, v11
	v_exp_f32_e32 v2, v2
	v_add_f32_e32 v4, 1.0, v4
	v_add_f32_e32 v24, 1.0, v24
	v_rcp_f32_e32 v191, v20
	v_add_f32_e32 v20, 1.0, v21
	v_rcp_f32_e32 v202, v4
	v_add_f32_e32 v4, 1.0, v5
	v_mul_f32_e32 v5, 0xbfb8aa3b, v6
	v_rcp_f32_e32 v185, v24
	v_add_f32_e32 v24, 1.0, v25
	v_mul_f32_e32 v25, 0xbfb8aa3b, v26
	v_rcp_f32_e32 v176, v20
	v_add_f32_e32 v20, 1.0, v22
	v_exp_f32_e32 v5, v5
	v_mul_f32_e32 v6, 0xbfb8aa3b, v7
	v_rcp_f32_e32 v207, v0
	v_add_f32_e32 v0, 1.0, v1
	s_cmp_eq_u32 s44, 1
	v_exp_f32_e32 v25, v25
	v_mul_f32_e32 v26, 0xbfb8aa3b, v27
	v_rcp_f32_e32 v178, v20
	v_exp_f32_e32 v6, v6
	v_rcp_f32_e32 v196, v0
	v_add_f32_e32 v0, 1.0, v2
	v_mov_b32_e32 v20, v198
	v_exp_f32_e32 v26, v26
	v_rcp_f32_e32 v197, v0
	s_cselect_b32 s12, s34, 0x1200
	s_cmp_lg_u32 s44, 0
	v_mul_f32_e32 v12, 0xbfb8aa3b, v12
	v_ashrrev_i32_e32 v21, 6, v20
	v_bfe_u32 v0, v20, 3, 3
	s_cselect_b32 s12, s12, 0x600
	v_lshl_or_b32 v0, v21, 3, v0
	v_mul_f32_e32 v16, 0xbfb8aa3b, v16
	v_exp_f32_e32 v12, v12
	v_mul_f32_e32 v13, 0xbfb8aa3b, v13
	v_rcp_f32_e32 v203, v4
	v_add_f32_e32 v4, 1.0, v5
	s_lshl_b32 s45, s12, 1
	v_lshrrev_b32_e32 v23, 1, v0
	v_rcp_f32_e32 v187, v24
	v_add_f32_e32 v24, 1.0, v25
	v_exp_f32_e32 v16, v16
	v_mul_f32_e32 v17, 0xbfb8aa3b, v17
	v_exp_f32_e32 v13, v13
	v_rcp_f32_e32 v188, v4
	v_add_f32_e32 v4, 1.0, v6
	s_add_u32 s12, s38, s45
	v_xor_b32_e32 v6, v23, v20
	v_rcp_f32_e32 v172, v24
	v_add_f32_e32 v24, 1.0, v26
	v_exp_f32_e32 v17, v17
	s_addc_u32 s13, s39, 0
	v_lshlrev_b32_e32 v6, 4, v6
	v_rcp_f32_e32 v174, v24
	v_mov_b64_e32 v[2:3], s[12:13]
	v_and_b32_e32 v64, 0x70, v6
	v_add_u32_e32 v6, 64, v0
	v_add_u32_e32 v24, 0x80, v0
	v_add_u32_e32 v25, 0xc0, v0
	v_add_f32_e32 v12, 1.0, v12
	v_rcp_f32_e32 v190, v4
	v_mad_i64_i32 v[4:5], s[12:13], v0, s35, v[2:3]
	v_mad_i64_i32 v[8:9], s[12:13], v6, s35, v[2:3]
	v_mad_i64_i32 v[10:11], s[12:13], v24, s35, v[2:3]
	v_mad_i64_i32 v[2:3], s[12:13], v25, s35, v[2:3]
	v_lshl_add_u32 v208, v21, 10, 0
	v_add_f32_e32 v16, 1.0, v16
	v_rcp_f32_e32 v200, v12
	v_add_f32_e32 v12, 1.0, v13
	v_mul_f32_e32 v13, 0xbfb8aa3b, v14
	v_readfirstlane_b32 s12, v208
	v_rcp_f32_e32 v193, v16
	v_add_f32_e32 v16, 1.0, v17
	v_mul_f32_e32 v17, 0xbfb8aa3b, v18
	v_exp_f32_e32 v13, v13
	v_mul_f32_e32 v14, 0xbfb8aa3b, v15
	v_lshl_add_u64 v[4:5], v[4:5], 0, v[64:65]
	s_mov_b32 m0, s12
	v_exp_f32_e32 v17, v17
	v_mul_f32_e32 v18, 0xbfb8aa3b, v19
	v_exp_f32_e32 v14, v14
	global_load_lds_dwordx4 v[4:5], off
	v_add_u32_e32 v4, 0x2000, v208
	v_exp_f32_e32 v18, v18
	v_readfirstlane_b32 s12, v4
	v_add_u32_e32 v4, 0x4000, v208
	v_lshl_add_u64 v[8:9], v[8:9], 0, v[64:65]
	s_mov_b32 m0, s12
	v_readfirstlane_b32 s12, v4
	v_add_u32_e32 v4, 0x6000, v208
	v_rcp_f32_e32 v201, v12
	v_add_f32_e32 v12, 1.0, v13
	s_lshl_b32 s46, s44, 20
	v_lshl_add_u64 v[10:11], v[10:11], 0, v[64:65]
	global_load_lds_dwordx4 v[8:9], off
	s_mov_b32 m0, s12
	v_readfirstlane_b32 s12, v4
	v_rcp_f32_e32 v195, v16
	v_add_f32_e32 v16, 1.0, v17
	v_rcp_f32_e32 v184, v12
	v_add_f32_e32 v12, 1.0, v14
	s_add_u32 s46, s40, s46
	v_ashrrev_i32_e32 v1, 31, v0
	v_lshl_add_u64 v[2:3], v[2:3], 0, v[64:65]
	global_load_lds_dwordx4 v[10:11], off
	s_mov_b32 m0, s12
	v_rcp_f32_e32 v180, v16
	v_add_f32_e32 v16, 1.0, v18
	v_rcp_f32_e32 v186, v12
	s_addc_u32 s47, s41, 0
	v_ashrrev_i32_e32 v7, 31, v6
	v_lshlrev_b64 v[12:13], 10, v[0:1]
	global_load_lds_dwordx4 v[2:3], off
	v_add_u32_e32 v2, 0x8000, v208
	v_rcp_f32_e32 v182, v16
	v_lshl_add_u64 v[14:15], s[46:47], 0, v[12:13]
	v_lshlrev_b64 v[16:17], 10, v[6:7]
	v_readfirstlane_b32 s12, v2
	v_add_u32_e32 v2, 0xa000, v208
	v_lshl_add_u64 v[14:15], v[14:15], 0, v[64:65]
	v_lshl_add_u64 v[18:19], s[46:47], 0, v[16:17]
	s_mov_b32 m0, s12
	v_readfirstlane_b32 s12, v2
	v_lshl_add_u64 v[18:19], v[18:19], 0, v[64:65]
	global_load_lds_dwordx4 v[14:15], off
	s_mov_b32 m0, s12
	v_mul_f32_e32 v60, 0xbfb8aa3b, v60
	global_load_lds_dwordx4 v[18:19], off
	v_mul_f32_e32 v56, 0xbfb8aa3b, v56
	v_mul_f32_e32 v52, 0xbfb8aa3b, v52
	v_mul_f32_e32 v48, 0xbfb8aa3b, v48
	v_mul_f32_e32 v44, 0xbfb8aa3b, v44
	v_mul_f32_e32 v40, 0xbfb8aa3b, v40
	v_mul_f32_e32 v36, 0xbfb8aa3b, v36
	v_mul_f32_e32 v32, 0xbfb8aa3b, v32
	v_mul_f32_e32 v28, 0xbfb8aa3b, v28
	v_exp_f32_e32 v60, v60
	v_mul_f32_e32 v61, 0xbfb8aa3b, v61
	v_exp_f32_e32 v56, v56
	v_mul_f32_e32 v57, 0xbfb8aa3b, v57
	v_exp_f32_e32 v52, v52
	v_mul_f32_e32 v53, 0xbfb8aa3b, v53
	v_exp_f32_e32 v48, v48
	v_mul_f32_e32 v49, 0xbfb8aa3b, v49
	v_exp_f32_e32 v44, v44
	v_mul_f32_e32 v45, 0xbfb8aa3b, v45
	v_exp_f32_e32 v40, v40
	v_mul_f32_e32 v41, 0xbfb8aa3b, v41
	v_exp_f32_e32 v36, v36
	v_mul_f32_e32 v37, 0xbfb8aa3b, v37
	v_exp_f32_e32 v32, v32
	v_mul_f32_e32 v33, 0xbfb8aa3b, v33
	v_exp_f32_e32 v28, v28
	v_mul_f32_e32 v29, 0xbfb8aa3b, v29
	v_exp_f32_e32 v61, v61
	v_exp_f32_e32 v57, v57
	v_exp_f32_e32 v53, v53
	v_exp_f32_e32 v49, v49
	v_exp_f32_e32 v45, v45
	v_exp_f32_e32 v41, v41
	v_exp_f32_e32 v37, v37
	v_exp_f32_e32 v33, v33
	v_exp_f32_e32 v29, v29
	v_lshrrev_b32_e32 v2, 31, v20
	v_add_u32_e32 v2, v21, v2
	v_add_f32_e32 v60, 1.0, v60
	v_add_f32_e32 v56, 1.0, v56
	v_add_f32_e32 v52, 1.0, v52
	v_add_f32_e32 v48, 1.0, v48
	v_add_f32_e32 v44, 1.0, v44
	v_add_f32_e32 v40, 1.0, v40
	v_add_f32_e32 v36, 1.0, v36
	v_add_f32_e32 v32, 1.0, v32
	v_add_f32_e32 v28, 1.0, v28
	v_bfe_u32 v1, v20, 4, 2
	v_bfe_u32 v7, v20, 1, 3
	v_and_b32_e32 v3, 0x7fffe, v2
	v_lshlrev_b32_e32 v2, 12, v2
	v_rcp_f32_e32 v149, v60
	v_add_f32_e32 v60, 1.0, v61
	v_mul_f32_e32 v61, 0xbfb8aa3b, v62
	v_rcp_f32_e32 v153, v56
	v_add_f32_e32 v56, 1.0, v57
	v_mul_f32_e32 v57, 0xbfb8aa3b, v58
	v_rcp_f32_e32 v157, v52
	v_add_f32_e32 v52, 1.0, v53
	v_mul_f32_e32 v53, 0xbfb8aa3b, v54
	v_rcp_f32_e32 v161, v48
	v_add_f32_e32 v48, 1.0, v49
	v_mul_f32_e32 v49, 0xbfb8aa3b, v50
	v_rcp_f32_e32 v165, v44
	v_add_f32_e32 v44, 1.0, v45
	v_mul_f32_e32 v45, 0xbfb8aa3b, v46
	v_rcp_f32_e32 v169, v40
	v_add_f32_e32 v40, 1.0, v41
	v_mul_f32_e32 v41, 0xbfb8aa3b, v42
	v_rcp_f32_e32 v173, v36
	v_add_f32_e32 v36, 1.0, v37
	v_mul_f32_e32 v37, 0xbfb8aa3b, v38
	v_rcp_f32_e32 v177, v32
	v_add_f32_e32 v32, 1.0, v33
	v_mul_f32_e32 v33, 0xbfb8aa3b, v34
	v_rcp_f32_e32 v181, v28
	v_add_f32_e32 v28, 1.0, v29
	v_mul_f32_e32 v29, 0xbfb8aa3b, v30
	v_and_b32_e32 v211, 0xffffe000, v2
	v_xor_b32_e32 v2, v1, v7
	v_bitop3_b32 v1, v1, v7, 4 bitop3:0x36
	v_exp_f32_e32 v61, v61
	v_mul_f32_e32 v62, 0xbfb8aa3b, v63
	v_exp_f32_e32 v57, v57
	v_mul_f32_e32 v58, 0xbfb8aa3b, v59
	v_exp_f32_e32 v53, v53
	v_mul_f32_e32 v54, 0xbfb8aa3b, v55
	v_exp_f32_e32 v49, v49
	v_mul_f32_e32 v50, 0xbfb8aa3b, v51
	v_exp_f32_e32 v45, v45
	v_mul_f32_e32 v46, 0xbfb8aa3b, v47
	v_exp_f32_e32 v41, v41
	v_mul_f32_e32 v42, 0xbfb8aa3b, v43
	v_exp_f32_e32 v37, v37
	v_mul_f32_e32 v38, 0xbfb8aa3b, v39
	v_exp_f32_e32 v33, v33
	v_mul_f32_e32 v34, 0xbfb8aa3b, v35
	v_exp_f32_e32 v29, v29
	v_mul_f32_e32 v30, 0xbfb8aa3b, v31
	v_lshlrev_b32_e32 v213, 4, v1
	v_bitop3_b32 v1, v23, 7, v20 bitop3:0x48
	v_exp_f32_e32 v62, v62
	v_exp_f32_e32 v58, v58
	v_exp_f32_e32 v54, v54
	v_exp_f32_e32 v50, v50
	v_exp_f32_e32 v46, v46
	v_exp_f32_e32 v42, v42
	v_exp_f32_e32 v38, v38
	v_exp_f32_e32 v34, v34
	v_exp_f32_e32 v30, v30
	v_lshlrev_b32_e32 v64, 4, v1
	v_mad_i64_i32 v[0:1], s[12:13], v0, s35, v[64:65]
	s_add_u32 s12, s42, s45
	v_rcp_f32_e32 v151, v60
	v_add_f32_e32 v60, 1.0, v61
	v_rcp_f32_e32 v155, v56
	v_add_f32_e32 v56, 1.0, v57
	v_rcp_f32_e32 v159, v52
	v_add_f32_e32 v52, 1.0, v53
	v_rcp_f32_e32 v163, v48
	v_add_f32_e32 v48, 1.0, v49
	v_rcp_f32_e32 v167, v44
	v_add_f32_e32 v44, 1.0, v45
	v_rcp_f32_e32 v171, v40
	v_add_f32_e32 v40, 1.0, v41
	v_rcp_f32_e32 v175, v36
	v_add_f32_e32 v36, 1.0, v37
	v_rcp_f32_e32 v179, v32
	v_add_f32_e32 v32, 1.0, v33
	v_rcp_f32_e32 v183, v28
	v_add_f32_e32 v28, 1.0, v29
	s_addc_u32 s13, s43, 0
	v_rcp_f32_e32 v142, v60
	v_add_f32_e32 v60, 1.0, v62
	v_rcp_f32_e32 v144, v56
	v_add_f32_e32 v56, 1.0, v58
	v_rcp_f32_e32 v146, v52
	v_add_f32_e32 v52, 1.0, v54
	v_rcp_f32_e32 v148, v48
	v_add_f32_e32 v48, 1.0, v50
	v_rcp_f32_e32 v152, v44
	v_add_f32_e32 v44, 1.0, v46
	v_rcp_f32_e32 v156, v40
	v_add_f32_e32 v40, 1.0, v42
	v_rcp_f32_e32 v160, v36
	v_add_f32_e32 v36, 1.0, v38
	v_rcp_f32_e32 v164, v32
	v_add_f32_e32 v32, 1.0, v34
	v_rcp_f32_e32 v168, v28
	v_add_f32_e32 v28, 1.0, v30
	v_lshl_add_u64 v[130:131], s[12:13], 0, v[0:1]
	v_mad_i64_i32 v[0:1], s[46:47], v6, s35, v[64:65]
	v_rcp_f32_e32 v143, v60
	v_rcp_f32_e32 v145, v56
	v_rcp_f32_e32 v147, v52
	v_rcp_f32_e32 v150, v48
	v_rcp_f32_e32 v154, v44
	v_rcp_f32_e32 v158, v40
	v_rcp_f32_e32 v162, v36
	v_rcp_f32_e32 v166, v32
	v_rcp_f32_e32 v170, v28
	v_lshl_add_u64 v[132:133], s[12:13], 0, v[0:1]
	v_mad_i64_i32 v[0:1], s[46:47], v24, s35, v[64:65]
	v_lshl_add_u64 v[134:135], s[12:13], 0, v[0:1]
	v_mad_i64_i32 v[0:1], s[46:47], v25, s35, v[64:65]
	v_and_b32_e32 v22, 15, v20
	v_sub_u32_e32 v3, v21, v3
	v_lshl_add_u64 v[136:137], s[12:13], 0, v[0:1]
	v_or_b32_e32 v12, v12, v64
	v_or_b32_e32 v16, v16, v64
	v_mov_b32_e32 v0, 0
	s_mov_b32 s3, 0
	v_lshlrev_b32_e32 v209, 13, v3
	v_lshlrev_b32_e32 v210, 7, v22
	v_lshlrev_b32_e32 v212, 4, v2
	v_lshl_add_u64 v[138:139], s[4:5], 0, v[12:13]
	v_lshl_add_u64 v[140:141], s[4:5], 0, v[16:17]
	s_mov_b64 s[12:13], 0
	v_mov_b32_e32 v1, v0
	v_mov_b32_e32 v2, v0
	v_mov_b32_e32 v3, v0
	v_mov_b32_e32 v4, v0
	v_mov_b32_e32 v5, v0
	v_mov_b32_e32 v6, v0
	v_mov_b32_e32 v7, v0
	v_mov_b32_e32 v8, v0
	v_mov_b32_e32 v9, v0
	v_mov_b32_e32 v10, v0
	v_mov_b32_e32 v11, v0
	v_mov_b32_e32 v12, v0
	v_mov_b32_e32 v13, v0
	v_mov_b32_e32 v14, v0
	v_mov_b32_e32 v15, v0
	v_mov_b32_e32 v16, v0
	v_mov_b32_e32 v17, v0
	v_mov_b32_e32 v18, v0
	v_mov_b32_e32 v19, v0
	v_mov_b32_e32 v20, v0
	v_mov_b32_e32 v21, v0
	v_mov_b32_e32 v22, v0
	v_mov_b32_e32 v23, v0
	v_mov_b32_e32 v24, v0
	v_mov_b32_e32 v25, v0
	v_mov_b32_e32 v26, v0
	v_mov_b32_e32 v27, v0
	v_mov_b32_e32 v28, v0
	v_mov_b32_e32 v29, v0
	v_mov_b32_e32 v30, v0
	v_mov_b32_e32 v31, v0
	v_mov_b32_e32 v32, v0
	v_mov_b32_e32 v33, v0
	v_mov_b32_e32 v34, v0
	v_mov_b32_e32 v35, v0
	v_mov_b32_e32 v36, v0
	v_mov_b32_e32 v37, v0
	v_mov_b32_e32 v38, v0
	v_mov_b32_e32 v39, v0
	v_mov_b32_e32 v40, v0
	v_mov_b32_e32 v41, v0
	v_mov_b32_e32 v42, v0
	v_mov_b32_e32 v43, v0
	v_mov_b32_e32 v44, v0
	v_mov_b32_e32 v45, v0
	v_mov_b32_e32 v46, v0
	v_mov_b32_e32 v47, v0
	v_mov_b32_e32 v48, v0
	v_mov_b32_e32 v49, v0
	v_mov_b32_e32 v50, v0
	v_mov_b32_e32 v51, v0
	v_mov_b32_e32 v52, v0
	v_mov_b32_e32 v53, v0
	v_mov_b32_e32 v54, v0
	v_mov_b32_e32 v55, v0
	v_mov_b32_e32 v56, v0
	v_mov_b32_e32 v57, v0
	v_mov_b32_e32 v58, v0
	v_mov_b32_e32 v59, v0
	v_mov_b32_e32 v60, v0
	v_mov_b32_e32 v61, v0
	v_mov_b32_e32 v62, v0
	v_mov_b32_e32 v63, v0
	v_readfirstlane_b32 s46, v208
	s_nop 1
	s_add_i32 s46, s46, 0xc000
	s_mov_b32 m0, s46
	s_nop 0
	global_load_lds_dwordx4 v[130:131], off
	s_add_i32 m0, s46, 0x2000
	s_nop 0
	global_load_lds_dwordx4 v[132:133], off
	s_add_i32 m0, s46, 0x4000
	s_nop 0
	global_load_lds_dwordx4 v[134:135], off
	s_add_i32 m0, s46, 0x6000
	s_nop 0
	global_load_lds_dwordx4 v[136:137], off
	s_add_i32 m0, s46, 0x8000
	s_nop 0
	global_load_lds_dwordx4 v[138:139], off
	s_add_i32 m0, s46, 0xa000
	s_nop 0
	global_load_lds_dwordx4 v[140:141], off
	s_waitcnt vmcnt(6) lgkmcnt(0)
	s_barrier
	s_branch .LBB0_1504
